# static s_setprio 1 for waves 4-7 across each attention tile loop (on top of loop-edge rotation)
# speedup vs baseline: 1.0460x; 1.0015x over previous
.LBB0_37:
	s_setprio 0
	v_mov_b64_e32 v[62:63], v[30:31]
	v_mov_b64_e32 v[60:61], v[28:29]
	v_mov_b64_e32 v[58:59], v[26:27]
	v_mov_b64_e32 v[56:57], v[24:25]
	v_mov_b64_e32 v[54:55], v[22:23]
	v_mov_b64_e32 v[52:53], v[20:21]
	v_mov_b64_e32 v[50:51], v[18:19]
	v_mov_b64_e32 v[48:49], v[16:17]
	v_mov_b64_e32 v[46:47], v[14:15]
	v_mov_b64_e32 v[44:45], v[12:13]
	v_mov_b64_e32 v[42:43], v[10:11]
	v_mov_b64_e32 v[40:41], v[8:9]
	v_mov_b64_e32 v[38:39], v[6:7]
	v_mov_b64_e32 v[36:37], v[4:5]
	v_mov_b64_e32 v[34:35], v[2:3]
	v_mov_b64_e32 v[32:33], v[0:1]
	v_mov_b32_e32 v0, v31

.LBB0_55:
	v_sub_u32_e64 v1, s40, v232 clamp
	s_min_u32 s30, s40, 0xe80
	s_addk_i32 s30, 0x180
	v_readfirstlane_b32 s31, v1
	s_lshr_b32 s35, s31, 6
	s_lshr_b32 s36, s30, 6
	s_and_b64 s[30:31], s[28:29], exec
	s_cselect_b32 s30, s41, s36
	s_cselect_b32 s40, 0, s35
	s_waitcnt vmcnt(0) lgkmcnt(0)
	s_barrier
	v_mov_b32_e32 v30, v0
	s_sub_i32 s41, s30, s40
	v_mov_b32_e32 v29, v0
	v_mov_b32_e32 v28, v0
	v_mov_b32_e32 v27, v0
	v_mov_b32_e32 v26, v0
	v_mov_b32_e32 v25, v0
	v_mov_b32_e32 v24, v0
	v_mov_b32_e32 v23, v0
	v_mov_b32_e32 v22, v0
	v_mov_b32_e32 v21, v0
	v_mov_b32_e32 v20, v0
	v_mov_b32_e32 v19, v0
	v_mov_b32_e32 v18, v0
	v_mov_b32_e32 v17, v0
	v_mov_b32_e32 v16, v0
	v_mov_b32_e32 v15, v0
	v_mov_b32_e32 v14, v0
	v_mov_b32_e32 v13, v0
	v_mov_b32_e32 v12, v0
	v_mov_b32_e32 v11, v0
	v_mov_b32_e32 v10, v0
	v_mov_b32_e32 v9, v0
	v_mov_b32_e32 v8, v0
	v_mov_b32_e32 v7, v0
	v_mov_b32_e32 v6, v0
	v_mov_b32_e32 v5, v0
	v_mov_b32_e32 v4, v0
	v_mov_b32_e32 v3, v0
	v_mov_b32_e32 v2, v0
	v_mov_b32_e32 v1, v0
	v_mov_b64_e32 v[62:63], v[30:31]
	s_cmp_gt_i32 s41, -4
	v_mov_b32_e32 v121, v113
	v_mov_b64_e32 v[32:33], v[0:1]
	v_mov_b64_e32 v[60:61], v[28:29]
	v_mov_b64_e32 v[58:59], v[26:27]
	v_mov_b64_e32 v[56:57], v[24:25]
	v_mov_b64_e32 v[54:55], v[22:23]
	v_mov_b64_e32 v[52:53], v[20:21]
	v_mov_b64_e32 v[50:51], v[18:19]
	v_mov_b64_e32 v[48:49], v[16:17]
	v_mov_b64_e32 v[46:47], v[14:15]
	v_mov_b64_e32 v[44:45], v[12:13]
	v_mov_b64_e32 v[42:43], v[10:11]
	v_mov_b64_e32 v[40:41], v[8:9]
	v_mov_b64_e32 v[38:39], v[6:7]
	v_mov_b64_e32 v[36:37], v[4:5]
	v_mov_b64_e32 v[34:35], v[2:3]
	s_cbranch_scc0 .LBB0_38
	s_lshl_b32 s42, s42, 12
	s_lshl_b32 s30, s43, 8
	s_add_i32 s41, s41, 4
	s_addk_i32 s42, 0xff00
	s_sub_i32 s30, 0, s30
	s_and_b64 s[28:29], s[28:29], exec
	s_cselect_b32 s28, 0xfffff000, s30
	s_lshl_b32 s29, s44, 7
	v_add_u32_e32 v123, s29, v112
	v_add_u32_e32 v125, s29, v114
	s_lshl_b32 s29, s40, 6
	s_add_i32 s29, s29, s28
	v_mov_b32_e32 v1, v0
	v_mov_b32_e32 v2, v0
	v_mov_b32_e32 v3, v0
	v_mov_b32_e32 v4, v0
	v_mov_b32_e32 v5, v0
	v_mov_b32_e32 v6, v0
	v_mov_b32_e32 v7, v0
	v_mov_b32_e32 v8, v0
	v_mov_b32_e32 v9, v0
	v_mov_b32_e32 v10, v0
	v_mov_b32_e32 v11, v0
	v_mov_b32_e32 v12, v0
	v_mov_b32_e32 v13, v0
	v_mov_b32_e32 v14, v0
	v_mov_b32_e32 v15, v0
	v_mov_b32_e32 v16, v0
	v_mov_b32_e32 v17, v0
	v_mov_b32_e32 v18, v0
	v_mov_b32_e32 v19, v0
	v_mov_b32_e32 v20, v0
	v_mov_b32_e32 v21, v0
	v_mov_b32_e32 v22, v0
	v_mov_b32_e32 v23, v0
	v_mov_b32_e32 v24, v0
	v_mov_b32_e32 v25, v0
	v_mov_b32_e32 v26, v0
	v_mov_b32_e32 v27, v0
	v_mov_b32_e32 v28, v0
	v_mov_b32_e32 v29, v0
	v_mov_b32_e32 v30, v0
	v_mov_b32_e32 v31, v0
	s_waitcnt vmcnt(0)
	v_mul_f32_e32 v131, 0x3fb8aa3b, v64
	v_sub_f32_e32 v154, 0, v131
	v_mov_b32_e32 v155, v154
	v_mov_b32_e32 v156, v154
	v_mov_b32_e32 v157, v154
	v_mov_b32_e32 v158, v154
	v_mov_b32_e32 v159, v154
	v_mov_b32_e32 v160, v154
	v_mov_b32_e32 v161, v154
	v_mov_b32_e32 v162, v154
	v_mov_b32_e32 v163, v154
	v_mov_b32_e32 v164, v154
	v_mov_b32_e32 v165, v154
	v_mov_b32_e32 v166, v154
	v_mov_b32_e32 v167, v154
	v_mov_b32_e32 v168, v154
	v_mov_b32_e32 v169, v154
	s_mov_b32 s43, 0
	v_add_u32_e32 v127, s29, v134
	s_add_i32 s44, s34, 0x80
	s_mov_b32 s45, 2
	s_mov_b32 s46, 1
	v_mov_b32_e32 v121, v113
	s_mov_b32 s48, 0
	s_mov_b32 s47, 0
	v_readfirstlane_b32 s30, v191
	s_lshr_b32 s30, s30, 8
	s_cmp_eq_u32 s30, 0
	s_cbranch_scc1 .Latt_swa_p0
	s_setprio 1
.Latt_swa_p0:
.LBB0_57:
	s_add_i32 s35, s47, 2
	s_cmp_ge_i32 s35, s41
	s_cselect_b64 s[28:29], -1, 0
	s_and_b64 vcc, exec, s[28:29]
	s_cbranch_vccnz .LBB0_70
	s_cmp_gt_u32 s47, 1
	s_mov_b64 s[36:37], -1
	s_cbranch_scc0 .LBB0_63
	s_add_i32 s35, s35, s40
	s_lshl_b32 s30, s35, 6
	s_add_i32 s34, s42, s30
	s_cbranch_execz .LBB0_64

.LBB0_88:
	s_setprio 0
	v_mov_b32_e32 v64, v157
	s_nop 1
	v_permlane32_swap_b32_e32 v157, v64
	v_add_f32_e32 v64, v157, v64
	v_div_scale_f32 v65, s[6:7], v64, v64, 1.0
	v_rcp_f32_e32 v66, v65
	s_ashr_i32 s39, s38, 31
	s_lshl_b64 s[6:7], s[38:39], 12
	s_add_u32 s8, s4, s6
	v_fma_f32 v67, -v65, v66, 1.0
	v_fmac_f32_e32 v66, v67, v66
	v_div_scale_f32 v67, vcc, 1.0, v64, 1.0
	v_mul_f32_e32 v68, v67, v66
	v_fma_f32 v69, -v65, v68, v67
	v_fmac_f32_e32 v68, v69, v66
	v_fma_f32 v65, -v65, v68, v67
	v_div_fmas_f32 v65, v65, v66, v68
	v_div_fixup_f32 v64, v65, v64, 1.0
	v_pk_mul_f32 v[0:1], v[0:1], v[64:65] op_sel_hi:[1,0]
	v_pk_mul_f32 v[2:3], v[2:3], v[64:65] op_sel_hi:[1,0]
	v_cvt_pk_bf16_f32 v0, v0, v1
	v_cvt_pk_bf16_f32 v1, v2, v3
	v_pk_mul_f32 v[2:3], v[4:5], v[64:65] op_sel_hi:[1,0]
	v_pk_mul_f32 v[4:5], v[6:7], v[64:65] op_sel_hi:[1,0]
	v_cvt_pk_bf16_f32 v2, v2, v3
	v_cvt_pk_bf16_f32 v3, v4, v5
	s_nop 0
	v_permlane32_swap_b32_e32 v0, v2
	v_permlane32_swap_b32_e32 v1, v3
	ds_write_b128 v175, v[0:3]
	v_pk_mul_f32 v[0:1], v[8:9], v[64:65] op_sel_hi:[1,0]
	v_pk_mul_f32 v[2:3], v[10:11], v[64:65] op_sel_hi:[1,0]
	v_cvt_pk_bf16_f32 v0, v0, v1
	v_cvt_pk_bf16_f32 v1, v2, v3
	v_pk_mul_f32 v[2:3], v[12:13], v[64:65] op_sel_hi:[1,0]
	v_pk_mul_f32 v[4:5], v[14:15], v[64:65] op_sel_hi:[1,0]
	v_cvt_pk_bf16_f32 v2, v2, v3
	v_cvt_pk_bf16_f32 v3, v4, v5
	s_nop 0
	v_permlane32_swap_b32_e32 v0, v2
	v_permlane32_swap_b32_e32 v1, v3
	ds_write_b128 v175, v[0:3] offset:32
	v_pk_mul_f32 v[0:1], v[48:49], v[64:65] op_sel_hi:[1,0]
	v_pk_mul_f32 v[2:3], v[50:51], v[64:65] op_sel_hi:[1,0]
	v_cvt_pk_bf16_f32 v0, v0, v1
	v_cvt_pk_bf16_f32 v1, v2, v3
	v_pk_mul_f32 v[2:3], v[52:53], v[64:65] op_sel_hi:[1,0]
	v_pk_mul_f32 v[4:5], v[54:55], v[64:65] op_sel_hi:[1,0]
	v_cvt_pk_bf16_f32 v2, v2, v3
	v_cvt_pk_bf16_f32 v3, v4, v5
	s_nop 0
	v_permlane32_swap_b32_e32 v0, v2
	v_permlane32_swap_b32_e32 v1, v3
	ds_write_b128 v175, v[0:3] offset:64
	v_pk_mul_f32 v[0:1], v[56:57], v[64:65] op_sel_hi:[1,0]
	v_pk_mul_f32 v[2:3], v[58:59], v[64:65] op_sel_hi:[1,0]
	v_cvt_pk_bf16_f32 v0, v0, v1
	v_cvt_pk_bf16_f32 v1, v2, v3
	v_pk_mul_f32 v[2:3], v[60:61], v[64:65] op_sel_hi:[1,0]
	v_pk_mul_f32 v[4:5], v[62:63], v[64:65] op_sel_hi:[1,0]
	v_cvt_pk_bf16_f32 v2, v2, v3
	v_cvt_pk_bf16_f32 v3, v4, v5
	s_nop 0
	v_permlane32_swap_b32_e32 v0, v2
	v_permlane32_swap_b32_e32 v1, v3
	ds_write_b128 v175, v[0:3] offset:96
	v_pk_mul_f32 v[0:1], v[32:33], v[64:65] op_sel_hi:[1,0]
	v_pk_mul_f32 v[2:3], v[34:35], v[64:65] op_sel_hi:[1,0]
	v_cvt_pk_bf16_f32 v0, v0, v1
	v_cvt_pk_bf16_f32 v1, v2, v3
	v_pk_mul_f32 v[2:3], v[36:37], v[64:65] op_sel_hi:[1,0]
	v_pk_mul_f32 v[4:5], v[38:39], v[64:65] op_sel_hi:[1,0]
	v_cvt_pk_bf16_f32 v2, v2, v3
	v_cvt_pk_bf16_f32 v3, v4, v5
	s_nop 0
	v_permlane32_swap_b32_e32 v0, v2
	v_permlane32_swap_b32_e32 v1, v3
	ds_write_b128 v175, v[0:3] offset:128
	v_pk_mul_f32 v[0:1], v[40:41], v[64:65] op_sel_hi:[1,0]
	v_pk_mul_f32 v[2:3], v[42:43], v[64:65] op_sel_hi:[1,0]
	v_cvt_pk_bf16_f32 v0, v0, v1
	v_cvt_pk_bf16_f32 v1, v2, v3
	v_pk_mul_f32 v[2:3], v[44:45], v[64:65] op_sel_hi:[1,0]
	v_pk_mul_f32 v[4:5], v[46:47], v[64:65] op_sel_hi:[1,0]
	v_cvt_pk_bf16_f32 v2, v2, v3
	v_cvt_pk_bf16_f32 v3, v4, v5
	s_nop 0
	v_permlane32_swap_b32_e32 v0, v2
	v_permlane32_swap_b32_e32 v1, v3
	ds_write_b128 v175, v[0:3] offset:160
	v_pk_mul_f32 v[0:1], v[16:17], v[64:65] op_sel_hi:[1,0]
	v_pk_mul_f32 v[2:3], v[18:19], v[64:65] op_sel_hi:[1,0]
	v_cvt_pk_bf16_f32 v0, v0, v1
	v_cvt_pk_bf16_f32 v1, v2, v3
	v_pk_mul_f32 v[2:3], v[20:21], v[64:65] op_sel_hi:[1,0]
	v_pk_mul_f32 v[4:5], v[22:23], v[64:65] op_sel_hi:[1,0]
	v_cvt_pk_bf16_f32 v2, v2, v3
	v_cvt_pk_bf16_f32 v3, v4, v5
	s_nop 0
	v_permlane32_swap_b32_e32 v0, v2
	v_permlane32_swap_b32_e32 v1, v3
	ds_write_b128 v175, v[0:3] offset:192
	v_pk_mul_f32 v[0:1], v[24:25], v[64:65] op_sel_hi:[1,0]
	v_pk_mul_f32 v[2:3], v[26:27], v[64:65] op_sel_hi:[1,0]
	v_cvt_pk_bf16_f32 v0, v0, v1
	v_cvt_pk_bf16_f32 v1, v2, v3
	v_pk_mul_f32 v[2:3], v[28:29], v[64:65] op_sel_hi:[1,0]
	v_pk_mul_f32 v[4:5], v[30:31], v[64:65] op_sel_hi:[1,0]
	v_cvt_pk_bf16_f32 v2, v2, v3
	v_cvt_pk_bf16_f32 v3, v4, v5
	s_nop 0
	v_permlane32_swap_b32_e32 v0, v2
	v_permlane32_swap_b32_e32 v1, v3
	ds_write_b128 v175, v[0:3] offset:224
	s_waitcnt lgkmcnt(0)
	s_addc_u32 s9, s5, s7
	s_ashr_i32 s45, s44, 31
	s_lshl_b64 s[6:7], s[44:45], 1
	ds_read_b128 v[0:3], v176
	ds_read_b128 v[4:7], v176 offset:1088
	s_add_u32 s6, s8, s6
	s_addc_u32 s7, s9, s7
	v_mov_b32_e32 v153, v129
	v_lshl_add_u64 v[8:9], s[6:7], 0, v[152:153]
	v_mov_b32_e32 v155, v129
	v_lshl_add_u64 v[10:11], v[8:9], 0, v[154:155]
	v_mov_b32_e32 v157, v129
	s_waitcnt lgkmcnt(0)
	global_store_dwordx4 v[10:11], v[0:3], off
	v_lshl_add_u64 v[10:11], v[8:9], 0, v[156:157]
	ds_read_b128 v[0:3], v176 offset:2176
	global_store_dwordx4 v[10:11], v[4:7], off
	ds_read_b128 v[4:7], v176 offset:3264
	v_mov_b32_e32 v159, v129
	v_lshl_add_u64 v[10:11], v[8:9], 0, v[158:159]
	v_mov_b32_e32 v161, v129
	s_waitcnt lgkmcnt(0)
	global_store_dwordx4 v[10:11], v[0:3], off
	v_lshl_add_u64 v[10:11], v[8:9], 0, v[160:161]
	ds_read_b128 v[0:3], v176 offset:4352
	global_store_dwordx4 v[10:11], v[4:7], off
	ds_read_b128 v[4:7], v176 offset:5440
	v_mov_b32_e32 v163, v129
	v_lshl_add_u64 v[10:11], v[8:9], 0, v[162:163]
	v_mov_b32_e32 v165, v129
	s_waitcnt lgkmcnt(0)
	global_store_dwordx4 v[10:11], v[0:3], off
	v_lshl_add_u64 v[10:11], v[8:9], 0, v[164:165]
	ds_read_b128 v[0:3], v176 offset:6528
	global_store_dwordx4 v[10:11], v[4:7], off
	ds_read_b128 v[4:7], v176 offset:7616
	v_mov_b32_e32 v167, v129
	v_lshl_add_u64 v[10:11], v[8:9], 0, v[166:167]
	v_mov_b32_e32 v169, v129
	s_waitcnt lgkmcnt(0)
	global_store_dwordx4 v[10:11], v[0:3], off
	s_add_i32 s20, s20, s67
	s_cmpk_gt_i32 s20, 0x87f
	v_lshl_add_u64 v[0:1], v[8:9], 0, v[168:169]
	global_store_dwordx4 v[0:1], v[4:7], off
	s_waitcnt lgkmcnt(0)
	s_barrier
	s_cbranch_scc1 .LBB0_133

.LBB0_106:
	v_mov_b32_e32 v14, v0
	v_mov_b32_e32 v15, v0
	s_waitcnt vmcnt(0) lgkmcnt(0)
	s_barrier
	v_mov_b32_e32 v1, v0
	v_mov_b32_e32 v2, v0
	v_mov_b32_e32 v3, v0
	v_mov_b32_e32 v4, v0
	v_mov_b32_e32 v5, v0
	v_mov_b32_e32 v6, v0
	v_mov_b32_e32 v7, v0
	v_mov_b32_e32 v8, v0
	v_mov_b32_e32 v9, v0
	v_mov_b32_e32 v10, v0
	v_mov_b32_e32 v11, v0
	v_mov_b32_e32 v12, v0
	v_mov_b32_e32 v13, v0
	s_lshl_b32 s30, s43, 12
	s_lshl_b32 s44, s48, 7
	v_mov_b64_e32 v[62:63], v[14:15]
	v_mov_b64_e32 v[46:47], v[14:15]
	v_mov_b64_e32 v[30:31], v[14:15]
	s_add_i32 s43, s30, 0xffffff80
	v_add_u32_e32 v153, s44, v171
	v_add_u32_e32 v155, s44, v172
	s_add_i32 s45, s46, 0x80
	s_mov_b32 s50, 2
	s_mov_b32 s51, 1
	s_mov_b32 s53, 0
	v_mov_b32_e32 v157, 0
	v_mov_b32_e32 v159, 0
	v_mov_b32_e32 v96, 0
	v_mov_b32_e32 v97, 0
	v_mov_b32_e32 v98, 0
	v_mov_b32_e32 v99, 0
	v_mov_b32_e32 v100, 0
	v_mov_b32_e32 v101, 0
	v_mov_b32_e32 v102, 0
	v_mov_b32_e32 v103, 0
	v_mov_b32_e32 v104, 0
	v_mov_b32_e32 v105, 0
	v_mov_b32_e32 v106, 0
	v_mov_b32_e32 v107, 0
	v_mov_b32_e32 v108, 0
	v_mov_b32_e32 v109, 0
	v_mov_b32_e32 v110, 0
	v_mov_b32_e32 v111, 0
	v_mov_b64_e32 v[60:61], v[12:13]
	v_mov_b64_e32 v[58:59], v[10:11]
	v_mov_b64_e32 v[56:57], v[8:9]
	v_mov_b64_e32 v[54:55], v[6:7]
	v_mov_b64_e32 v[52:53], v[4:5]
	v_mov_b64_e32 v[50:51], v[2:3]
	v_mov_b64_e32 v[48:49], v[0:1]
	v_mov_b64_e32 v[44:45], v[12:13]
	v_mov_b64_e32 v[42:43], v[10:11]
	v_mov_b64_e32 v[40:41], v[8:9]
	v_mov_b64_e32 v[38:39], v[6:7]
	v_mov_b64_e32 v[36:37], v[4:5]
	v_mov_b64_e32 v[34:35], v[2:3]
	v_mov_b64_e32 v[32:33], v[0:1]
	v_mov_b64_e32 v[28:29], v[12:13]
	v_mov_b64_e32 v[26:27], v[10:11]
	v_mov_b64_e32 v[24:25], v[8:9]
	v_mov_b64_e32 v[22:23], v[6:7]
	v_mov_b64_e32 v[20:21], v[4:5]
	v_mov_b64_e32 v[18:19], v[2:3]
	v_mov_b64_e32 v[16:17], v[0:1]
	s_mov_b32 s52, 0
	s_waitcnt vmcnt(0)
	v_readfirstlane_b32 s30, v191
	s_lshr_b32 s30, s30, 8
	s_cmp_eq_u32 s30, 0
	s_cbranch_scc1 .Latt_diff_p0
	s_setprio 1
.Latt_diff_p0:
.LBB0_107:
	s_add_i32 s30, s52, 2
	s_cmp_ge_u32 s30, s21
	s_cselect_b64 s[46:47], -1, 0
	s_and_b64 vcc, exec, s[46:47]
	s_cbranch_vccnz .LBB0_116
	s_cmp_lt_u32 s52, 2
	s_mul_i32 s55, s50, 0x2400
	s_cselect_b32 s48, s45, s43
	s_and_b64 vcc, exec, s[6:7]
	s_add_i32 s56, s55, 0
	s_cbranch_vccnz .LBB0_110
	s_add_i32 m0, s56, s41
	v_lshl_add_u32 v244, s48, 12, v153
	global_load_lds_dwordx4 v244, s[18:19]

.LBB0_153:
	s_setprio 0
	v_mov_b32_e32 v64, v205
	s_nop 1
	v_permlane32_swap_b32_e32 v205, v64
	v_add_f32_e32 v64, v205, v64
	v_div_scale_f32 v65, s[6:7], v64, v64, 1.0
	v_rcp_f32_e32 v66, v65
	s_ashr_i32 s49, s48, 31
	s_lshl_b64 s[6:7], s[48:49], 11
	s_add_u32 s8, s5, s6
	v_fma_f32 v67, -v65, v66, 1.0
	v_fmac_f32_e32 v66, v67, v66
	v_div_scale_f32 v67, vcc, 1.0, v64, 1.0
	v_mul_f32_e32 v68, v67, v66
	v_fma_f32 v69, -v65, v68, v67
	v_fmac_f32_e32 v68, v69, v66
	v_fma_f32 v65, -v65, v68, v67
	v_div_fmas_f32 v65, v65, v66, v68
	v_div_fixup_f32 v64, v65, v64, 1.0
	v_pk_mul_f32 v[48:49], v[48:49], v[64:65] op_sel_hi:[1,0]
	v_pk_mul_f32 v[50:51], v[50:51], v[64:65] op_sel_hi:[1,0]
	v_pk_mul_f32 v[32:33], v[32:33], v[64:65] op_sel_hi:[1,0]
	v_pk_mul_f32 v[34:35], v[34:35], v[64:65] op_sel_hi:[1,0]
	v_pk_mul_f32 v[16:17], v[16:17], v[64:65] op_sel_hi:[1,0]
	v_pk_mul_f32 v[18:19], v[18:19], v[64:65] op_sel_hi:[1,0]
	v_pk_mul_f32 v[0:1], v[0:1], v[64:65] op_sel_hi:[1,0]
	v_pk_mul_f32 v[2:3], v[2:3], v[64:65] op_sel_hi:[1,0]
	v_cvt_pk_bf16_f32 v48, v48, v49
	v_cvt_pk_bf16_f32 v49, v50, v51
	v_pk_mul_f32 v[50:51], v[52:53], v[64:65] op_sel_hi:[1,0]
	v_pk_mul_f32 v[52:53], v[54:55], v[64:65] op_sel_hi:[1,0]
	v_cvt_pk_bf16_f32 v32, v32, v33
	v_cvt_pk_bf16_f32 v33, v34, v35
	v_pk_mul_f32 v[34:35], v[36:37], v[64:65] op_sel_hi:[1,0]
	v_pk_mul_f32 v[36:37], v[38:39], v[64:65] op_sel_hi:[1,0]
	v_cvt_pk_bf16_f32 v16, v16, v17
	v_cvt_pk_bf16_f32 v17, v18, v19
	v_pk_mul_f32 v[18:19], v[20:21], v[64:65] op_sel_hi:[1,0]
	v_pk_mul_f32 v[20:21], v[22:23], v[64:65] op_sel_hi:[1,0]
	v_cvt_pk_bf16_f32 v0, v0, v1
	v_cvt_pk_bf16_f32 v1, v2, v3
	v_pk_mul_f32 v[2:3], v[4:5], v[64:65] op_sel_hi:[1,0]
	v_pk_mul_f32 v[4:5], v[6:7], v[64:65] op_sel_hi:[1,0]
	v_cvt_pk_bf16_f32 v50, v50, v51
	v_cvt_pk_bf16_f32 v51, v52, v53
	v_cvt_pk_bf16_f32 v34, v34, v35
	v_cvt_pk_bf16_f32 v35, v36, v37
	v_cvt_pk_bf16_f32 v18, v18, v19
	v_cvt_pk_bf16_f32 v19, v20, v21
	v_cvt_pk_bf16_f32 v2, v2, v3
	v_cvt_pk_bf16_f32 v3, v4, v5
	v_permlane32_swap_b32_e32 v48, v50
	v_permlane32_swap_b32_e32 v49, v51
	v_permlane32_swap_b32_e32 v32, v34
	v_permlane32_swap_b32_e32 v33, v35
	v_permlane32_swap_b32_e32 v16, v18
	v_permlane32_swap_b32_e32 v17, v19
	v_permlane32_swap_b32_e32 v0, v2
	v_permlane32_swap_b32_e32 v1, v3
	ds_write_b128 v248, v[48:51]
	v_pk_mul_f32 v[48:49], v[56:57], v[64:65] op_sel_hi:[1,0]
	v_pk_mul_f32 v[50:51], v[58:59], v[64:65] op_sel_hi:[1,0]
	ds_write_b128 v248, v[32:35] offset:64
	v_pk_mul_f32 v[32:33], v[40:41], v[64:65] op_sel_hi:[1,0]
	v_pk_mul_f32 v[34:35], v[42:43], v[64:65] op_sel_hi:[1,0]
	ds_write_b128 v248, v[16:19] offset:128
	v_pk_mul_f32 v[16:17], v[24:25], v[64:65] op_sel_hi:[1,0]
	v_pk_mul_f32 v[18:19], v[26:27], v[64:65] op_sel_hi:[1,0]
	ds_write_b128 v248, v[0:3] offset:192
	v_pk_mul_f32 v[0:1], v[8:9], v[64:65] op_sel_hi:[1,0]
	v_pk_mul_f32 v[2:3], v[10:11], v[64:65] op_sel_hi:[1,0]
	v_cvt_pk_bf16_f32 v48, v48, v49
	v_cvt_pk_bf16_f32 v49, v50, v51
	v_pk_mul_f32 v[50:51], v[60:61], v[64:65] op_sel_hi:[1,0]
	v_pk_mul_f32 v[52:53], v[62:63], v[64:65] op_sel_hi:[1,0]
	v_cvt_pk_bf16_f32 v32, v32, v33
	v_cvt_pk_bf16_f32 v33, v34, v35
	v_pk_mul_f32 v[34:35], v[44:45], v[64:65] op_sel_hi:[1,0]
	v_pk_mul_f32 v[36:37], v[46:47], v[64:65] op_sel_hi:[1,0]
	v_cvt_pk_bf16_f32 v16, v16, v17
	v_cvt_pk_bf16_f32 v17, v18, v19
	v_pk_mul_f32 v[18:19], v[28:29], v[64:65] op_sel_hi:[1,0]
	v_pk_mul_f32 v[20:21], v[30:31], v[64:65] op_sel_hi:[1,0]
	v_cvt_pk_bf16_f32 v0, v0, v1
	v_cvt_pk_bf16_f32 v1, v2, v3
	v_pk_mul_f32 v[2:3], v[12:13], v[64:65] op_sel_hi:[1,0]
	v_pk_mul_f32 v[4:5], v[14:15], v[64:65] op_sel_hi:[1,0]
	v_cvt_pk_bf16_f32 v50, v50, v51
	v_cvt_pk_bf16_f32 v51, v52, v53
	v_cvt_pk_bf16_f32 v34, v34, v35
	v_cvt_pk_bf16_f32 v35, v36, v37
	v_cvt_pk_bf16_f32 v18, v18, v19
	v_cvt_pk_bf16_f32 v19, v20, v21
	v_cvt_pk_bf16_f32 v2, v2, v3
	v_cvt_pk_bf16_f32 v3, v4, v5
	v_permlane32_swap_b32_e32 v48, v50
	v_permlane32_swap_b32_e32 v49, v51
	v_permlane32_swap_b32_e32 v32, v34
	v_permlane32_swap_b32_e32 v33, v35
	v_permlane32_swap_b32_e32 v16, v18
	v_permlane32_swap_b32_e32 v17, v19
	v_permlane32_swap_b32_e32 v0, v2
	v_permlane32_swap_b32_e32 v1, v3
	ds_write_b128 v248, v[48:51] offset:32
	ds_write_b128 v248, v[32:35] offset:96
	ds_write_b128 v248, v[16:19] offset:160
	ds_write_b128 v248, v[0:3] offset:224
	s_waitcnt lgkmcnt(0)
	s_addc_u32 s9, s40, s7
	s_ashr_i32 s51, s50, 31
	s_lshl_b64 s[6:7], s[50:51], 1
	ds_read_b128 v[0:3], v249
	ds_read_b128 v[4:7], v249 offset:1088
	s_add_u32 s6, s8, s6
	s_addc_u32 s7, s9, s7
	v_mov_b32_e32 v205, v129
	v_lshl_add_u64 v[8:9], s[6:7], 0, v[204:205]
	v_mov_b32_e32 v207, v129
	v_lshl_add_u64 v[10:11], v[8:9], 0, v[206:207]
	v_mov_b32_e32 v209, v129
	s_waitcnt lgkmcnt(0)
	global_store_dwordx4 v[10:11], v[0:3], off
	v_lshl_add_u64 v[10:11], v[8:9], 0, v[208:209]
	ds_read_b128 v[0:3], v249 offset:2176
	global_store_dwordx4 v[10:11], v[4:7], off
	ds_read_b128 v[4:7], v249 offset:3264
	v_mov_b32_e32 v211, v129
	v_lshl_add_u64 v[10:11], v[8:9], 0, v[210:211]
	v_mov_b32_e32 v213, v129
	s_waitcnt lgkmcnt(0)
	global_store_dwordx4 v[10:11], v[0:3], off
	v_lshl_add_u64 v[10:11], v[8:9], 0, v[212:213]
	ds_read_b128 v[0:3], v249 offset:4352
	global_store_dwordx4 v[10:11], v[4:7], off
	ds_read_b128 v[4:7], v249 offset:5440
	v_mov_b32_e32 v215, v129
	v_lshl_add_u64 v[10:11], v[8:9], 0, v[214:215]
	v_mov_b32_e32 v217, v129
	s_waitcnt lgkmcnt(0)
	global_store_dwordx4 v[10:11], v[0:3], off
	v_lshl_add_u64 v[10:11], v[8:9], 0, v[216:217]
	ds_read_b128 v[0:3], v249 offset:6528
	global_store_dwordx4 v[10:11], v[4:7], off
	ds_read_b128 v[4:7], v249 offset:7616
	v_mov_b32_e32 v219, v129
	v_lshl_add_u64 v[10:11], v[8:9], 0, v[218:219]
	v_mov_b32_e32 v221, v129
	s_waitcnt lgkmcnt(0)
	global_store_dwordx4 v[10:11], v[0:3], off
	s_add_i32 s94, s94, s67
	s_cmp_ge_i32 s94, s0
	v_lshl_add_u64 v[0:1], v[8:9], 0, v[220:221]
	global_store_dwordx4 v[0:1], v[4:7], off
	s_waitcnt lgkmcnt(0)
	s_barrier
	s_cbranch_scc1 .LBB0_210

.LBB0_177:
	v_mov_b32_e32 v14, v0
	v_mov_b32_e32 v15, v0
	s_waitcnt vmcnt(0) lgkmcnt(0)
	s_barrier
	v_mov_b32_e32 v1, v0
	v_mov_b32_e32 v2, v0
	v_mov_b32_e32 v3, v0
	v_mov_b32_e32 v4, v0
	v_mov_b32_e32 v5, v0
	v_mov_b32_e32 v6, v0
	v_mov_b32_e32 v7, v0
	v_mov_b32_e32 v8, v0
	v_mov_b32_e32 v9, v0
	v_mov_b32_e32 v10, v0
	v_mov_b32_e32 v11, v0
	v_mov_b32_e32 v12, v0
	v_mov_b32_e32 v13, v0
	s_lshl_b32 s49, s49, 12
	v_mov_b64_e32 v[30:31], v[14:15]
	v_mov_b64_e32 v[46:47], v[14:15]
	v_mov_b64_e32 v[62:63], v[14:15]
	v_mad_u64_u32 v[222:223], s[30:31], s50, v238, v[190:191]
	v_mad_u64_u32 v[224:225], s[30:31], s50, v240, v[192:193]
	v_mad_u64_u32 v[226:227], s[30:31], s50, v242, v[194:195]
	v_mad_u64_u32 v[228:229], s[30:31], s50, v244, v[196:197]
	s_addk_i32 s49, 0xff80
	s_add_i32 s51, s60, 0x80
	s_mov_b32 s52, 2
	s_mov_b32 s53, 1
	s_mov_b32 s56, 0
	v_mov_b32_e32 v205, 0
	v_mov_b32_e32 v207, 0
	v_mov_b32_e32 v96, 0
	v_mov_b32_e32 v97, 0
	v_mov_b32_e32 v98, 0
	v_mov_b32_e32 v99, 0
	v_mov_b32_e32 v100, 0
	v_mov_b32_e32 v101, 0
	v_mov_b32_e32 v102, 0
	v_mov_b32_e32 v103, 0
	v_mov_b32_e32 v104, 0
	v_mov_b32_e32 v105, 0
	v_mov_b32_e32 v106, 0
	v_mov_b32_e32 v107, 0
	v_mov_b32_e32 v108, 0
	v_mov_b32_e32 v109, 0
	v_mov_b32_e32 v110, 0
	v_mov_b32_e32 v111, 0
	v_mov_b64_e32 v[28:29], v[12:13]
	v_mov_b64_e32 v[26:27], v[10:11]
	v_mov_b64_e32 v[24:25], v[8:9]
	v_mov_b64_e32 v[22:23], v[6:7]
	v_mov_b64_e32 v[20:21], v[4:5]
	v_mov_b64_e32 v[18:19], v[2:3]
	v_mov_b64_e32 v[16:17], v[0:1]
	v_mov_b64_e32 v[44:45], v[12:13]
	v_mov_b64_e32 v[42:43], v[10:11]
	v_mov_b64_e32 v[40:41], v[8:9]
	v_mov_b64_e32 v[38:39], v[6:7]
	v_mov_b64_e32 v[36:37], v[4:5]
	v_mov_b64_e32 v[34:35], v[2:3]
	v_mov_b64_e32 v[32:33], v[0:1]
	v_mov_b64_e32 v[60:61], v[12:13]
	v_mov_b64_e32 v[58:59], v[10:11]
	v_mov_b64_e32 v[56:57], v[8:9]
	v_mov_b64_e32 v[54:55], v[6:7]
	v_mov_b64_e32 v[52:53], v[4:5]
	v_mov_b64_e32 v[50:51], v[2:3]
	v_mov_b64_e32 v[48:49], v[0:1]
	s_mov_b32 s55, 0
	s_waitcnt vmcnt(0)
	v_readfirstlane_b32 s30, v191
	s_lshr_b32 s30, s30, 8
	s_cmp_eq_u32 s30, 0
	s_cbranch_scc1 .Latt_mla_p0
	s_setprio 1
.Latt_mla_p0:
.LBB0_178:
	s_add_i32 s30, s55, 2
	s_cmp_ge_u32 s30, s20
	s_cselect_b64 s[60:61], -1, 0
	s_and_b64 vcc, exec, s[60:61]
	s_cbranch_vccnz .LBB0_191
	s_cmp_lt_u32 s55, 2
	s_mul_i32 s30, s52, 0x6400
	s_cselect_b32 s62, s51, s49
	s_and_b64 vcc, exec, s[6:7]
	s_add_i32 s57, s30, 0
	s_cbranch_vccnz .LBB0_184
	s_add_i32 m0, s57, s42
	v_mad_u64_u32 v[250:251], s[30:31], s62, v237, v[222:223]
	global_load_lds_dwordx4 v250, s[2:3]
	s_and_b64 vcc, exec, s[8:9]
	s_cbranch_vccz .LBB0_185
